# k10 + MoBA step: first K-fragment ds_reads issued before the tile-prefetch DMA block (LDS latency overlaps DMA issue); byte-neutral reorder
# speedup vs baseline: 1.0000x; 1.0000x over previous
.LBB0_467:
	s_add_i32 s0, s18, 35
	v_mov_b32_e32 v1, v77
	v_add_u32_e32 v90, s22, v185
	v_add_u32_e32 v70, v90, v186
	ds_read_b128 v[66:69], v70
	ds_read_b128 v[82:85], v70 offset:8192
	v_cmp_ge_i32_e64 s[40:41], s0, v184
	v_cmp_lt_i32_e32 vcc, s0, v184
	s_and_saveexec_b64 s[0:1], vcc
	s_cbranch_execz .LBB0_469
	s_add_i32 s12, s26, s19
	v_lshl_add_u64 v[92:93], v[172:173], 0, v[170:171]
	s_mov_b32 m0, s12
	s_nop 0
	global_load_lds_dwordx4 v[92:93], off
	v_lshl_add_u64 v[92:93], v[172:173], 0, v[174:175]
	s_add_i32 m0, s12, 0x400
	s_nop 0
	global_load_lds_dwordx4 v[92:93], off
	s_add_i32 m0, s12, 0x4000
	v_lshl_add_u64 v[92:93], v[172:173], 0, v[176:177]
	global_load_lds_dwordx4 v[92:93], off
	v_lshl_add_u64 v[92:93], v[172:173], 0, v[178:179]
	s_add_i32 m0, s12, 0x4400
	s_nop 0
	global_load_lds_dwordx4 v[92:93], off
.LBB0_469:
	s_or_b64 exec, exec, s[0:1]
	v_add_u32_e32 v86, v90, v187
	s_lshr_b32 s0, s3, 8
	v_cmp_ge_i32_e32 vcc, s0, v181
	s_waitcnt lgkmcnt(0)
	v_mfma_f32_32x32x16_bf16 v[66:81], v[66:69], v[130:133], 0
	s_lshl_b32 s0, 1, s0
	v_cmp_lt_i32_e64 s[44:45], s50, v195
	v_mfma_f32_32x32x16_bf16 v[114:129], v[82:85], v[130:133], 0
	ds_read_b128 v[82:85], v86
	ds_read_b128 v[86:89], v86 offset:8192
	s_waitcnt lgkmcnt(0)
	v_mfma_f32_32x32x16_bf16 v[66:81], v[82:85], v[134:137], v[66:81]
	v_mfma_f32_32x32x16_bf16 v[114:129], v[86:89], v[134:137], v[114:129]
	v_add_u32_e32 v86, v90, v188
	ds_read_b128 v[82:85], v86
	ds_read_b128 v[86:89], v86 offset:8192
	s_waitcnt lgkmcnt(0)
	v_mfma_f32_32x32x16_bf16 v[66:81], v[82:85], v[138:141], v[66:81]
	v_mfma_f32_32x32x16_bf16 v[114:129], v[86:89], v[138:141], v[114:129]
	v_add_u32_e32 v86, v90, v189
	ds_read_b128 v[82:85], v86
	ds_read_b128 v[86:89], v86 offset:8192
	s_waitcnt lgkmcnt(0)
	v_mfma_f32_32x32x16_bf16 v[66:81], v[82:85], v[142:145], v[66:81]
	v_mfma_f32_32x32x16_bf16 v[114:129], v[86:89], v[142:145], v[114:129]
	v_add_u32_e32 v86, v90, v190
	ds_read_b128 v[82:85], v86
	ds_read_b128 v[86:89], v86 offset:8192
	s_waitcnt lgkmcnt(0)
	v_mfma_f32_32x32x16_bf16 v[66:81], v[82:85], v[146:149], v[66:81]
	v_mfma_f32_32x32x16_bf16 v[114:129], v[86:89], v[146:149], v[114:129]
	v_add_u32_e32 v86, v90, v191
	ds_read_b128 v[82:85], v86
	ds_read_b128 v[86:89], v86 offset:8192
	s_waitcnt lgkmcnt(0)
	v_mfma_f32_32x32x16_bf16 v[66:81], v[82:85], v[150:153], v[66:81]
	v_mfma_f32_32x32x16_bf16 v[114:129], v[86:89], v[150:153], v[114:129]
	v_add_u32_e32 v86, v90, v192
	ds_read_b128 v[82:85], v86
	ds_read_b128 v[86:89], v86 offset:8192
	s_waitcnt lgkmcnt(0)
	v_mfma_f32_32x32x16_bf16 v[66:81], v[82:85], v[154:157], v[66:81]
	v_mfma_f32_32x32x16_bf16 v[114:129], v[86:89], v[154:157], v[114:129]
	v_add_u32_e32 v86, v90, v193
	ds_read_b128 v[82:85], v86
	ds_read_b128 v[86:89], v86 offset:8192
	s_waitcnt lgkmcnt(0)
	v_mfma_f32_32x32x16_bf16 v[66:81], v[82:85], v[158:161], v[66:81]
	v_and_b32_e32 v82, s0, v169
	v_cmp_ne_u32_e64 s[42:43], 0, v82
	s_or_b64 s[12:13], vcc, s[42:43]
	v_cmp_gt_i32_e64 s[42:43], s3, v194
	v_cmp_le_i32_e32 vcc, s3, v194
	s_or_b64 s[0:1], s[42:43], s[44:45]
	v_mfma_f32_32x32x16_bf16 v[114:129], v[86:89], v[158:161], v[114:129]
	s_and_saveexec_b64 s[14:15], s[0:1]
	s_xor_b64 s[0:1], exec, s[14:15]
	s_cbranch_execz .LBB0_474
	s_and_b64 s[28:29], vcc, s[12:13]
	v_mov_b32_e32 v82, 0xff800000
	s_and_saveexec_b64 s[14:15], s[28:29]
	s_cbranch_execz .LBB0_472
	v_readlane_b32 s23, v254, 54
	s_nop 1
	v_mov_b32_e32 v82, s23
	ds_read_b32 v82, v82
